# pool W=4 row loop branch-free as well (on top of v30)
# baseline (speedup 1.0000x reference)
; __device__ __forceinline__ void pool_item(LAS unsigned char* lds, const bf16_t* Z, bf16_t* Y, const bf16_t* PW, const float* pscale, const int tile, const int g) {
;     ...
;       if (g == 0) { POOL_ROWS(2) } else if (g == 1) { POOL_ROWS(4) } else if (g == 2) { POOL_ROWS(8) } else { POOL_ROWS(16) }
.LBB0_293:
	v_add_u32_e32 v8, s6, v5
	v_add_u32_e32 v11, 0x11cc0, v8
	ds_read_b32 v20, v11
	ds_read_b32 v21, v11 offset:272
	ds_read_b32 v22, v11 offset:544
	ds_read_b32 v23, v11 offset:816
	v_min_u32_e32 v1, 3, v6
	v_add_u32_e32 v1, 1, v1
	v_cvt_f32_ubyte0_e32 v1, v1
	s_addk_i32 s6, 0x110
	s_waitcnt lgkmcnt(0)
	v_lshlrev_b32_e32 v3, 16, v20
	v_and_b32_e32 v2, 0xffff0000, v20
	v_pk_add_f32 v[2:3], v[2:3], 0 op_sel_hi:[1,0]
	v_lshlrev_b32_e32 v11, 16, v21
	v_and_b32_e32 v10, 0xffff0000, v21
	v_add_f32_e32 v2, v2, v10
	v_add_f32_e32 v3, v3, v11
	v_lshlrev_b32_e32 v11, 16, v22
	v_and_b32_e32 v10, 0xffff0000, v22
	v_add_f32_e32 v2, v2, v10
	v_add_f32_e32 v3, v3, v11
	v_and_b32_e32 v10, 0xffff0000, v23
	v_lshlrev_b32_e32 v9, 16, v23
	v_add_f32_e32 v3, v3, v9
	v_div_scale_f32 v11, s[4:5], v1, v1, v3
	v_rcp_f32_e32 v12, v11
	v_add_f32_e32 v2, v2, v10
	v_add_u32_e32 v6, 1, v6
	s_cmpk_eq_i32 s6, 0x2200
	v_fma_f32 v13, -v11, v12, 1.0
	v_fmac_f32_e32 v12, v13, v12
	v_div_scale_f32 v13, vcc, v3, v1, v3
	v_mul_f32_e32 v14, v13, v12
	v_fma_f32 v15, -v11, v14, v13
	v_fmac_f32_e32 v14, v15, v12
	v_fma_f32 v11, -v11, v14, v13
	v_div_fmas_f32 v11, v11, v12, v14
	v_div_fixup_f32 v3, v11, v1, v3
	v_sub_f32_e32 v3, v3, v9
	v_div_scale_f32 v9, s[4:5], v1, v1, v2
	v_rcp_f32_e32 v11, v9
	s_nop 0
	v_fma_f32 v12, -v9, v11, 1.0
	v_fmac_f32_e32 v11, v12, v11
	v_div_scale_f32 v12, vcc, v2, v1, v2
	v_mul_f32_e32 v13, v12, v11
	v_fma_f32 v14, -v9, v13, v12
	v_fmac_f32_e32 v13, v14, v11
	v_fma_f32 v9, -v9, v13, v12
	v_div_fmas_f32 v9, v9, v11, v13
	v_div_fixup_f32 v1, v9, v1, v2
	v_sub_f32_e32 v1, v1, v10
	v_cvt_pk_bf16_f32 v1, v3, v1
	ds_write_b32 v8, v1
	s_cbranch_scc0 .LBB0_293
	s_branch .LBB0_193
